# speedup vs baseline: 1.0378x; 1.0367x over previous
; #define ARGMAX_STEP(CTRL) { const float ov = dppf<CTRL>(best); const int oc = dppi<CTRL>(bc);                \
;           const bool take = ov > best || (ov == best && oc < bc); best = take ? ov : best; bc = take ? oc : bc; }
; static __device__ __forceinline__ void phase_peer(const Params& p, char* smraw) {
;     ...
;   for (int t = blockIdx.x * 4 + w; t < T; t += gridDim.x * 4) {
;     const float* x1 = X1 + (size_t)t * 1024;
;     const float rs = ((const float*)(p.ws + WS_RSQQ))[t];
;     {
;       const int head = lane >> 3, g = lane & 7;
;       const float* tvp = TV + ((size_t)t * 16 + head * 2) * 16;
;       float cand[7]; int ccode[7];
; #pragma unroll
;       for (int m = 0; m < 7; ++m) {
;         ccode[m] = pkc[m];
;         cand[m] = ccode[m] == 255 ? -3.0e38f : tvp[ccode[m] >> 4] + tvp[16 + (ccode[m] & 15)];
;       }
;       float myv[2] = {0.f, 0.f}; int myc[2] = {0, 0}; float vmax = 0.f;
; #pragma unroll
;       for (int round = 0; round < 16; ++round) {
;         float best = cand[0]; int bc = ccode[0];
; #pragma unroll
;         for (int m = 1; m < 7; ++m) if (cand[m] > best) { best = cand[m]; bc = ccode[m]; }
;     ...
;         ARGMAX_STEP(0xB1) ARGMAX_STEP(0x4E) ARGMAX_STEP(0x141)
.LBB0_754:
	v_readlane_b32 s36, v224, 33
	v_ashrrev_i32_e32 v57, 31, v56
	v_readlane_b32 s37, v224, 34
	v_mov_b32_e32 v4, 0xff61b1e6
	s_nop 0
	v_lshl_add_u64 v[0:1], v[56:57], 2, s[36:37]
	global_load_dword v36, v[0:1], off
	v_lshlrev_b64 v[0:1], 8, v[56:57]
	v_or_b32_e32 v0, v0, v60
	v_lshlrev_b32_e32 v2, 2, v0
	v_add_u32_e32 v12, v2, v72
	v_add_u32_e32 v19, v2, v70
	v_add_u32_e32 v13, v2, v76
	v_add_u32_e32 v20, v2, v74
	v_add_u32_e32 v14, v2, v80
	v_add_u32_e32 v21, v2, v78
	v_add_u32_e32 v15, v2, v84
	v_add_u32_e32 v22, v2, v82
	v_add_u32_e32 v16, v2, v88
	v_add_u32_e32 v23, v2, v86
	v_add_u32_e32 v17, v2, v92
	v_add_u32_e32 v24, v2, v90
	v_add_u32_e32 v18, v2, v96
	v_add_u32_e32 v25, v2, v94
	global_load_dword v12, v12, s[44:45]
	global_load_dword v19, v19, s[44:45] offset:64
	global_load_dword v13, v13, s[44:45]
	global_load_dword v20, v20, s[44:45] offset:64
	global_load_dword v14, v14, s[44:45]
	global_load_dword v21, v21, s[44:45] offset:64
	global_load_dword v15, v15, s[44:45]
	global_load_dword v22, v22, s[44:45] offset:64
	global_load_dword v16, v16, s[44:45]
	global_load_dword v23, v23, s[44:45] offset:64
	global_load_dword v17, v17, s[44:45]
	global_load_dword v24, v24, s[44:45] offset:64
	global_load_dword v18, v18, s[44:45]
	global_load_dword v25, v25, s[44:45] offset:64
	s_waitcnt vmcnt(0)
	v_add_f32_e32 v4, v12, v19
	v_add_f32_e32 v5, v13, v20
	v_add_f32_e32 v8, v14, v21
	v_add_f32_e32 v7, v15, v22
	v_add_f32_e32 v10, v16, v23
	v_add_f32_e32 v9, v17, v24
	v_add_f32_e32 v11, v18, v25
	v_cndmask_b32_e64 v4, v201, v4, s[20:21]
	v_cndmask_b32_e64 v5, v201, v5, s[22:23]
	v_cndmask_b32_e64 v8, v201, v8, s[24:25]
	v_cndmask_b32_e64 v7, v201, v7, s[26:27]
	v_cndmask_b32_e64 v10, v201, v10, s[28:29]
	v_cndmask_b32_e64 v9, v201, v9, s[30:31]
	v_cndmask_b32_e64 v11, v201, v11, s[34:35]
	v_sub_u32_e32 v12, 0xff, v61
	v_ashrrev_i32_e32 v30, 31, v4
	v_or_b32_e32 v30, 0x80000000, v30
	v_xor_b32_e32 v13, v4, v30
	v_sub_u32_e32 v14, 0xff, v175
	v_ashrrev_i32_e32 v30, 31, v5
	v_or_b32_e32 v30, 0x80000000, v30
	v_xor_b32_e32 v15, v5, v30
	v_sub_u32_e32 v16, 0xff, v180
	v_ashrrev_i32_e32 v30, 31, v8
	v_or_b32_e32 v30, 0x80000000, v30
	v_xor_b32_e32 v17, v8, v30
	v_sub_u32_e32 v18, 0xff, v181
	v_ashrrev_i32_e32 v30, 31, v7
	v_or_b32_e32 v30, 0x80000000, v30
	v_xor_b32_e32 v19, v7, v30
	v_sub_u32_e32 v20, 0xff, v182
	v_ashrrev_i32_e32 v30, 31, v10
	v_or_b32_e32 v30, 0x80000000, v30
	v_xor_b32_e32 v21, v10, v30
	v_sub_u32_e32 v22, 0xff, v183
	v_ashrrev_i32_e32 v30, 31, v9
	v_or_b32_e32 v30, 0x80000000, v30
	v_xor_b32_e32 v23, v9, v30
	v_sub_u32_e32 v24, 0xff, v184
	v_ashrrev_i32_e32 v30, 31, v11
	v_or_b32_e32 v30, 0x80000000, v30
	v_xor_b32_e32 v25, v11, v30
	v_cmp_gt_u64_e32 vcc, v[24:25], v[12:13]
	s_and_saveexec_b64 s[36:37], vcc
	v_swap_b32 v12, v24
	v_swap_b32 v13, v25
	s_mov_b64 exec, s[36:37]
	v_cmp_gt_u64_e32 vcc, v[18:19], v[16:17]
	s_and_saveexec_b64 s[36:37], vcc
	v_swap_b32 v16, v18
	v_swap_b32 v17, v19
	s_mov_b64 exec, s[36:37]
	v_cmp_gt_u64_e32 vcc, v[22:23], v[20:21]
	s_and_saveexec_b64 s[36:37], vcc
	v_swap_b32 v20, v22
	v_swap_b32 v21, v23
	s_mov_b64 exec, s[36:37]
	v_cmp_gt_u64_e32 vcc, v[16:17], v[12:13]
	s_and_saveexec_b64 s[36:37], vcc
	v_swap_b32 v12, v16
	v_swap_b32 v13, v17
	s_mov_b64 exec, s[36:37]
	v_cmp_gt_u64_e32 vcc, v[20:21], v[14:15]
	s_and_saveexec_b64 s[36:37], vcc
	v_swap_b32 v14, v20
	v_swap_b32 v15, v21
	s_mov_b64 exec, s[36:37]
	v_cmp_gt_u64_e32 vcc, v[24:25], v[18:19]
	s_and_saveexec_b64 s[36:37], vcc
	v_swap_b32 v18, v24
	v_swap_b32 v19, v25
	s_mov_b64 exec, s[36:37]
	v_cmp_gt_u64_e32 vcc, v[14:15], v[12:13]
	s_and_saveexec_b64 s[36:37], vcc
	v_swap_b32 v12, v14
	v_swap_b32 v13, v15
	s_mov_b64 exec, s[36:37]
	v_cmp_gt_u64_e32 vcc, v[22:23], v[16:17]
	s_and_saveexec_b64 s[36:37], vcc
	v_swap_b32 v16, v22
	v_swap_b32 v17, v23
	s_mov_b64 exec, s[36:37]
	v_cmp_gt_u64_e32 vcc, v[20:21], v[18:19]
	s_and_saveexec_b64 s[36:37], vcc
	v_swap_b32 v18, v20
	v_swap_b32 v19, v21
	s_mov_b64 exec, s[36:37]
	v_cmp_gt_u64_e32 vcc, v[16:17], v[14:15]
	s_and_saveexec_b64 s[36:37], vcc
	v_swap_b32 v14, v16
	v_swap_b32 v15, v17
	s_mov_b64 exec, s[36:37]
	v_cmp_gt_u64_e32 vcc, v[24:25], v[20:21]
	s_and_saveexec_b64 s[36:37], vcc
	v_swap_b32 v20, v24
	v_swap_b32 v21, v25
	s_mov_b64 exec, s[36:37]
	v_cmp_gt_u64_e32 vcc, v[18:19], v[16:17]
	s_and_saveexec_b64 s[36:37], vcc
	v_swap_b32 v16, v18
	v_swap_b32 v17, v19
	s_mov_b64 exec, s[36:37]
	v_cmp_gt_u64_e32 vcc, v[22:23], v[20:21]
	s_and_saveexec_b64 s[36:37], vcc
	v_swap_b32 v20, v22
	v_swap_b32 v21, v23
	s_mov_b64 exec, s[36:37]
	v_cmp_gt_u64_e32 vcc, v[16:17], v[14:15]
	s_and_saveexec_b64 s[36:37], vcc
	v_swap_b32 v14, v16
	v_swap_b32 v15, v17
	s_mov_b64 exec, s[36:37]
	v_cmp_gt_u64_e32 vcc, v[20:21], v[18:19]
	s_and_saveexec_b64 s[36:37], vcc
	v_swap_b32 v18, v20
	v_swap_b32 v19, v21
	s_mov_b64 exec, s[36:37]
	v_cmp_gt_u64_e32 vcc, v[24:25], v[22:23]
	s_and_saveexec_b64 s[36:37], vcc
	v_swap_b32 v22, v24
	v_swap_b32 v23, v25
	s_mov_b64 exec, s[36:37]
	s_nop 1
	v_mov_b32_dpp v28, v12 quad_perm:[1,0,3,2] row_mask:0xf bank_mask:0xf bound_ctrl:1
	v_mov_b32_dpp v29, v13 quad_perm:[1,0,3,2] row_mask:0xf bank_mask:0xf bound_ctrl:1
	v_cmp_gt_u64_e32 vcc, v[28:29], v[12:13]
	s_nop 1
	v_cndmask_b32_e32 v26, v12, v28, vcc
	v_cndmask_b32_e32 v27, v13, v29, vcc
	s_nop 1
	v_mov_b32_dpp v28, v26 quad_perm:[2,3,0,1] row_mask:0xf bank_mask:0xf bound_ctrl:1
	v_mov_b32_dpp v29, v27 quad_perm:[2,3,0,1] row_mask:0xf bank_mask:0xf bound_ctrl:1
	v_cmp_gt_u64_e32 vcc, v[28:29], v[26:27]
	s_nop 1
	v_cndmask_b32_e32 v26, v26, v28, vcc
	v_cndmask_b32_e32 v27, v27, v29, vcc
	s_nop 1
; #define ARGMAX_STEP(CTRL) { const float ov = dppf<CTRL>(best); const int oc = dppi<CTRL>(bc);                \
;           const bool take = ov > best || (ov == best && oc < bc); best = take ? ov : best; bc = take ? oc : bc; }
; static __device__ __forceinline__ void phase_peer(const Params& p, char* smraw) {
;     ...
;       for (int round = 0; round < 16; ++round) {
;         float best = cand[0]; int bc = ccode[0];
; #pragma unroll
;         for (int m = 1; m < 7; ++m) if (cand[m] > best) { best = cand[m]; bc = ccode[m]; }
;     ...
;         ARGMAX_STEP(0xB1) ARGMAX_STEP(0x4E) ARGMAX_STEP(0x141)
;     ...
; #pragma unroll
;         for (int m = 0; m < 7; ++m) cand[m] = ccode[m] == bc ? -3.0e38f : cand[m];
;         if (round == 0) vmax = best;
;         if ((round & 7) == g) { myv[round >> 3] = best; myc[round >> 3] = bc; }
;       }
	v_mov_b32_dpp v28, v26 row_half_mirror row_mask:0xf bank_mask:0xf bound_ctrl:1
	v_mov_b32_dpp v29, v27 row_half_mirror row_mask:0xf bank_mask:0xf bound_ctrl:1
	v_cmp_gt_u64_e32 vcc, v[28:29], v[26:27]
	s_nop 1
	v_cndmask_b32_e32 v26, v26, v28, vcc
	v_cndmask_b32_e32 v27, v27, v29, vcc
	v_mov_b32_e32 v38, v27
	v_cndmask_b32_e64 v32, v32, v26, s[2:3]
	v_cndmask_b32_e64 v33, v33, v27, s[2:3]
	v_cmp_eq_u64_e32 vcc, v[12:13], v[26:27]
	s_and_saveexec_b64 s[36:37], vcc
	v_mov_b64_e32 v[12:13], v[14:15]
	v_mov_b64_e32 v[14:15], v[16:17]
	v_mov_b64_e32 v[16:17], v[18:19]
	v_mov_b64_e32 v[18:19], v[20:21]
	v_mov_b64_e32 v[20:21], v[22:23]
	v_mov_b64_e32 v[22:23], v[24:25]
	v_mov_b64_e32 v[24:25], 0
	s_mov_b64 exec, s[36:37]
	v_mov_b32_dpp v28, v12 quad_perm:[1,0,3,2] row_mask:0xf bank_mask:0xf bound_ctrl:1
	v_mov_b32_dpp v29, v13 quad_perm:[1,0,3,2] row_mask:0xf bank_mask:0xf bound_ctrl:1
	v_cmp_gt_u64_e32 vcc, v[28:29], v[12:13]
	s_nop 1
	v_cndmask_b32_e32 v26, v12, v28, vcc
	v_cndmask_b32_e32 v27, v13, v29, vcc
	s_nop 1
	v_mov_b32_dpp v28, v26 quad_perm:[2,3,0,1] row_mask:0xf bank_mask:0xf bound_ctrl:1
	v_mov_b32_dpp v29, v27 quad_perm:[2,3,0,1] row_mask:0xf bank_mask:0xf bound_ctrl:1
	v_cmp_gt_u64_e32 vcc, v[28:29], v[26:27]
	s_nop 1
	v_cndmask_b32_e32 v26, v26, v28, vcc
	v_cndmask_b32_e32 v27, v27, v29, vcc
	s_nop 1
	v_mov_b32_dpp v28, v26 row_half_mirror row_mask:0xf bank_mask:0xf bound_ctrl:1
	v_mov_b32_dpp v29, v27 row_half_mirror row_mask:0xf bank_mask:0xf bound_ctrl:1
	v_cmp_gt_u64_e32 vcc, v[28:29], v[26:27]
	s_nop 1
	v_cndmask_b32_e32 v26, v26, v28, vcc
	v_cndmask_b32_e32 v27, v27, v29, vcc
	v_cndmask_b32_e64 v32, v32, v26, s[4:5]
	v_cndmask_b32_e64 v33, v33, v27, s[4:5]
	v_cmp_eq_u64_e32 vcc, v[12:13], v[26:27]
	s_and_saveexec_b64 s[36:37], vcc
	v_mov_b64_e32 v[12:13], v[14:15]
	v_mov_b64_e32 v[14:15], v[16:17]
	v_mov_b64_e32 v[16:17], v[18:19]
	v_mov_b64_e32 v[18:19], v[20:21]
	v_mov_b64_e32 v[20:21], v[22:23]
	v_mov_b64_e32 v[22:23], v[24:25]
	v_mov_b64_e32 v[24:25], 0
	s_mov_b64 exec, s[36:37]
	v_mov_b32_dpp v28, v12 quad_perm:[1,0,3,2] row_mask:0xf bank_mask:0xf bound_ctrl:1
	v_mov_b32_dpp v29, v13 quad_perm:[1,0,3,2] row_mask:0xf bank_mask:0xf bound_ctrl:1
	v_cmp_gt_u64_e32 vcc, v[28:29], v[12:13]
	s_nop 1
	v_cndmask_b32_e32 v26, v12, v28, vcc
	v_cndmask_b32_e32 v27, v13, v29, vcc
	s_nop 1
	v_mov_b32_dpp v28, v26 quad_perm:[2,3,0,1] row_mask:0xf bank_mask:0xf bound_ctrl:1
	v_mov_b32_dpp v29, v27 quad_perm:[2,3,0,1] row_mask:0xf bank_mask:0xf bound_ctrl:1
	v_cmp_gt_u64_e32 vcc, v[28:29], v[26:27]
	s_nop 1
	v_cndmask_b32_e32 v26, v26, v28, vcc
	v_cndmask_b32_e32 v27, v27, v29, vcc
	s_nop 1
	v_mov_b32_dpp v28, v26 row_half_mirror row_mask:0xf bank_mask:0xf bound_ctrl:1
	v_mov_b32_dpp v29, v27 row_half_mirror row_mask:0xf bank_mask:0xf bound_ctrl:1
	v_cmp_gt_u64_e32 vcc, v[28:29], v[26:27]
	s_nop 1
	v_cndmask_b32_e32 v26, v26, v28, vcc
	v_cndmask_b32_e32 v27, v27, v29, vcc
	v_cndmask_b32_e64 v32, v32, v26, s[6:7]
	v_cndmask_b32_e64 v33, v33, v27, s[6:7]
	v_cmp_eq_u64_e32 vcc, v[12:13], v[26:27]
	s_and_saveexec_b64 s[36:37], vcc
	v_mov_b64_e32 v[12:13], v[14:15]
	v_mov_b64_e32 v[14:15], v[16:17]
	v_mov_b64_e32 v[16:17], v[18:19]
	v_mov_b64_e32 v[18:19], v[20:21]
	v_mov_b64_e32 v[20:21], v[22:23]
	v_mov_b64_e32 v[22:23], v[24:25]
	v_mov_b64_e32 v[24:25], 0
	s_mov_b64 exec, s[36:37]
	v_mov_b32_dpp v28, v12 quad_perm:[1,0,3,2] row_mask:0xf bank_mask:0xf bound_ctrl:1
	v_mov_b32_dpp v29, v13 quad_perm:[1,0,3,2] row_mask:0xf bank_mask:0xf bound_ctrl:1
	v_cmp_gt_u64_e32 vcc, v[28:29], v[12:13]
	s_nop 1
	v_cndmask_b32_e32 v26, v12, v28, vcc
	v_cndmask_b32_e32 v27, v13, v29, vcc
	s_nop 1
	v_mov_b32_dpp v28, v26 quad_perm:[2,3,0,1] row_mask:0xf bank_mask:0xf bound_ctrl:1
	v_mov_b32_dpp v29, v27 quad_perm:[2,3,0,1] row_mask:0xf bank_mask:0xf bound_ctrl:1
	v_cmp_gt_u64_e32 vcc, v[28:29], v[26:27]
	s_nop 1
	v_cndmask_b32_e32 v26, v26, v28, vcc
	v_cndmask_b32_e32 v27, v27, v29, vcc
	s_nop 1
	v_mov_b32_dpp v28, v26 row_half_mirror row_mask:0xf bank_mask:0xf bound_ctrl:1
	v_mov_b32_dpp v29, v27 row_half_mirror row_mask:0xf bank_mask:0xf bound_ctrl:1
	v_cmp_gt_u64_e32 vcc, v[28:29], v[26:27]
	s_nop 1
	v_cndmask_b32_e32 v26, v26, v28, vcc
	v_cndmask_b32_e32 v27, v27, v29, vcc
	v_cndmask_b32_e64 v32, v32, v26, s[8:9]
	v_cndmask_b32_e64 v33, v33, v27, s[8:9]
	v_cmp_eq_u64_e32 vcc, v[12:13], v[26:27]
	s_and_saveexec_b64 s[36:37], vcc
	v_mov_b64_e32 v[12:13], v[14:15]
	v_mov_b64_e32 v[14:15], v[16:17]
	v_mov_b64_e32 v[16:17], v[18:19]
	v_mov_b64_e32 v[18:19], v[20:21]
	v_mov_b64_e32 v[20:21], v[22:23]
	v_mov_b64_e32 v[22:23], v[24:25]
	v_mov_b64_e32 v[24:25], 0
	s_mov_b64 exec, s[36:37]
	v_mov_b32_dpp v28, v12 quad_perm:[1,0,3,2] row_mask:0xf bank_mask:0xf bound_ctrl:1
	v_mov_b32_dpp v29, v13 quad_perm:[1,0,3,2] row_mask:0xf bank_mask:0xf bound_ctrl:1
	v_cmp_gt_u64_e32 vcc, v[28:29], v[12:13]
	s_nop 1
	v_cndmask_b32_e32 v26, v12, v28, vcc
	v_cndmask_b32_e32 v27, v13, v29, vcc
	s_nop 1
	v_mov_b32_dpp v28, v26 quad_perm:[2,3,0,1] row_mask:0xf bank_mask:0xf bound_ctrl:1
	v_mov_b32_dpp v29, v27 quad_perm:[2,3,0,1] row_mask:0xf bank_mask:0xf bound_ctrl:1
	v_cmp_gt_u64_e32 vcc, v[28:29], v[26:27]
	s_nop 1
	v_cndmask_b32_e32 v26, v26, v28, vcc
	v_cndmask_b32_e32 v27, v27, v29, vcc
	s_nop 1
	v_mov_b32_dpp v28, v26 row_half_mirror row_mask:0xf bank_mask:0xf bound_ctrl:1
	v_mov_b32_dpp v29, v27 row_half_mirror row_mask:0xf bank_mask:0xf bound_ctrl:1
	v_cmp_gt_u64_e32 vcc, v[28:29], v[26:27]
	s_nop 1
	v_cndmask_b32_e32 v26, v26, v28, vcc
	v_cndmask_b32_e32 v27, v27, v29, vcc
	v_cndmask_b32_e64 v32, v32, v26, s[10:11]
	v_cndmask_b32_e64 v33, v33, v27, s[10:11]
; #define ARGMAX_STEP(CTRL) { const float ov = dppf<CTRL>(best); const int oc = dppi<CTRL>(bc);                \
;           const bool take = ov > best || (ov == best && oc < bc); best = take ? ov : best; bc = take ? oc : bc; }
; static __device__ __forceinline__ void phase_peer(const Params& p, char* smraw) {
;     ...
;       for (int round = 0; round < 16; ++round) {
;         float best = cand[0]; int bc = ccode[0];
; #pragma unroll
;         for (int m = 1; m < 7; ++m) if (cand[m] > best) { best = cand[m]; bc = ccode[m]; }
;     ...
;         ARGMAX_STEP(0xB1) ARGMAX_STEP(0x4E) ARGMAX_STEP(0x141)
;     ...
; #pragma unroll
;         for (int m = 0; m < 7; ++m) cand[m] = ccode[m] == bc ? -3.0e38f : cand[m];
;         if (round == 0) vmax = best;
;         if ((round & 7) == g) { myv[round >> 3] = best; myc[round >> 3] = bc; }
;       }
	v_cmp_eq_u64_e32 vcc, v[12:13], v[26:27]
	s_and_saveexec_b64 s[36:37], vcc
	v_mov_b64_e32 v[12:13], v[14:15]
	v_mov_b64_e32 v[14:15], v[16:17]
	v_mov_b64_e32 v[16:17], v[18:19]
	v_mov_b64_e32 v[18:19], v[20:21]
	v_mov_b64_e32 v[20:21], v[22:23]
	v_mov_b64_e32 v[22:23], v[24:25]
	v_mov_b64_e32 v[24:25], 0
	s_mov_b64 exec, s[36:37]
	v_mov_b32_dpp v28, v12 quad_perm:[1,0,3,2] row_mask:0xf bank_mask:0xf bound_ctrl:1
	v_mov_b32_dpp v29, v13 quad_perm:[1,0,3,2] row_mask:0xf bank_mask:0xf bound_ctrl:1
	v_cmp_gt_u64_e32 vcc, v[28:29], v[12:13]
	s_nop 1
	v_cndmask_b32_e32 v26, v12, v28, vcc
	v_cndmask_b32_e32 v27, v13, v29, vcc
	s_nop 1
	v_mov_b32_dpp v28, v26 quad_perm:[2,3,0,1] row_mask:0xf bank_mask:0xf bound_ctrl:1
	v_mov_b32_dpp v29, v27 quad_perm:[2,3,0,1] row_mask:0xf bank_mask:0xf bound_ctrl:1
	v_cmp_gt_u64_e32 vcc, v[28:29], v[26:27]
	s_nop 1
	v_cndmask_b32_e32 v26, v26, v28, vcc
	v_cndmask_b32_e32 v27, v27, v29, vcc
	s_nop 1
	v_mov_b32_dpp v28, v26 row_half_mirror row_mask:0xf bank_mask:0xf bound_ctrl:1
	v_mov_b32_dpp v29, v27 row_half_mirror row_mask:0xf bank_mask:0xf bound_ctrl:1
	v_cmp_gt_u64_e32 vcc, v[28:29], v[26:27]
	s_nop 1
	v_cndmask_b32_e32 v26, v26, v28, vcc
	v_cndmask_b32_e32 v27, v27, v29, vcc
	v_cndmask_b32_e64 v32, v32, v26, s[12:13]
	v_cndmask_b32_e64 v33, v33, v27, s[12:13]
	v_cmp_eq_u64_e32 vcc, v[12:13], v[26:27]
	s_and_saveexec_b64 s[36:37], vcc
	v_mov_b64_e32 v[12:13], v[14:15]
	v_mov_b64_e32 v[14:15], v[16:17]
	v_mov_b64_e32 v[16:17], v[18:19]
	v_mov_b64_e32 v[18:19], v[20:21]
	v_mov_b64_e32 v[20:21], v[22:23]
	v_mov_b64_e32 v[22:23], v[24:25]
	v_mov_b64_e32 v[24:25], 0
	s_mov_b64 exec, s[36:37]
	v_mov_b32_dpp v28, v12 quad_perm:[1,0,3,2] row_mask:0xf bank_mask:0xf bound_ctrl:1
	v_mov_b32_dpp v29, v13 quad_perm:[1,0,3,2] row_mask:0xf bank_mask:0xf bound_ctrl:1
	v_cmp_gt_u64_e32 vcc, v[28:29], v[12:13]
	s_nop 1
	v_cndmask_b32_e32 v26, v12, v28, vcc
	v_cndmask_b32_e32 v27, v13, v29, vcc
	s_nop 1
	v_mov_b32_dpp v28, v26 quad_perm:[2,3,0,1] row_mask:0xf bank_mask:0xf bound_ctrl:1
	v_mov_b32_dpp v29, v27 quad_perm:[2,3,0,1] row_mask:0xf bank_mask:0xf bound_ctrl:1
	v_cmp_gt_u64_e32 vcc, v[28:29], v[26:27]
	s_nop 1
	v_cndmask_b32_e32 v26, v26, v28, vcc
	v_cndmask_b32_e32 v27, v27, v29, vcc
	s_nop 1
	v_mov_b32_dpp v28, v26 row_half_mirror row_mask:0xf bank_mask:0xf bound_ctrl:1
	v_mov_b32_dpp v29, v27 row_half_mirror row_mask:0xf bank_mask:0xf bound_ctrl:1
	v_cmp_gt_u64_e32 vcc, v[28:29], v[26:27]
	s_nop 1
	v_cndmask_b32_e32 v26, v26, v28, vcc
	v_cndmask_b32_e32 v27, v27, v29, vcc
	v_cndmask_b32_e64 v32, v32, v26, s[14:15]
	v_cndmask_b32_e64 v33, v33, v27, s[14:15]
	v_cmp_eq_u64_e32 vcc, v[12:13], v[26:27]
	s_and_saveexec_b64 s[36:37], vcc
	v_mov_b64_e32 v[12:13], v[14:15]
	v_mov_b64_e32 v[14:15], v[16:17]
	v_mov_b64_e32 v[16:17], v[18:19]
	v_mov_b64_e32 v[18:19], v[20:21]
	v_mov_b64_e32 v[20:21], v[22:23]
	v_mov_b64_e32 v[22:23], v[24:25]
	v_mov_b64_e32 v[24:25], 0
	s_mov_b64 exec, s[36:37]
	v_mov_b32_dpp v28, v12 quad_perm:[1,0,3,2] row_mask:0xf bank_mask:0xf bound_ctrl:1
	v_mov_b32_dpp v29, v13 quad_perm:[1,0,3,2] row_mask:0xf bank_mask:0xf bound_ctrl:1
	v_cmp_gt_u64_e32 vcc, v[28:29], v[12:13]
	s_nop 1
	v_cndmask_b32_e32 v26, v12, v28, vcc
	v_cndmask_b32_e32 v27, v13, v29, vcc
	s_nop 1
	v_mov_b32_dpp v28, v26 quad_perm:[2,3,0,1] row_mask:0xf bank_mask:0xf bound_ctrl:1
	v_mov_b32_dpp v29, v27 quad_perm:[2,3,0,1] row_mask:0xf bank_mask:0xf bound_ctrl:1
	v_cmp_gt_u64_e32 vcc, v[28:29], v[26:27]
	s_nop 1
	v_cndmask_b32_e32 v26, v26, v28, vcc
	v_cndmask_b32_e32 v27, v27, v29, vcc
	s_nop 1
	v_mov_b32_dpp v28, v26 row_half_mirror row_mask:0xf bank_mask:0xf bound_ctrl:1
	v_mov_b32_dpp v29, v27 row_half_mirror row_mask:0xf bank_mask:0xf bound_ctrl:1
	v_cmp_gt_u64_e32 vcc, v[28:29], v[26:27]
	s_nop 1
	v_cndmask_b32_e32 v26, v26, v28, vcc
	v_cndmask_b32_e32 v27, v27, v29, vcc
	v_cndmask_b32_e64 v32, v32, v26, s[16:17]
	v_cndmask_b32_e64 v33, v33, v27, s[16:17]
	v_cmp_eq_u64_e32 vcc, v[12:13], v[26:27]
	s_and_saveexec_b64 s[36:37], vcc
	v_mov_b64_e32 v[12:13], v[14:15]
	v_mov_b64_e32 v[14:15], v[16:17]
	v_mov_b64_e32 v[16:17], v[18:19]
	v_mov_b64_e32 v[18:19], v[20:21]
	v_mov_b64_e32 v[20:21], v[22:23]
	v_mov_b64_e32 v[22:23], v[24:25]
	v_mov_b64_e32 v[24:25], 0
	s_mov_b64 exec, s[36:37]
	v_mov_b32_dpp v28, v12 quad_perm:[1,0,3,2] row_mask:0xf bank_mask:0xf bound_ctrl:1
	v_mov_b32_dpp v29, v13 quad_perm:[1,0,3,2] row_mask:0xf bank_mask:0xf bound_ctrl:1
	v_cmp_gt_u64_e32 vcc, v[28:29], v[12:13]
	s_nop 1
	v_cndmask_b32_e32 v26, v12, v28, vcc
	v_cndmask_b32_e32 v27, v13, v29, vcc
	s_nop 1
	v_mov_b32_dpp v28, v26 quad_perm:[2,3,0,1] row_mask:0xf bank_mask:0xf bound_ctrl:1
	v_mov_b32_dpp v29, v27 quad_perm:[2,3,0,1] row_mask:0xf bank_mask:0xf bound_ctrl:1
	v_cmp_gt_u64_e32 vcc, v[28:29], v[26:27]
	s_nop 1
	v_cndmask_b32_e32 v26, v26, v28, vcc
	v_cndmask_b32_e32 v27, v27, v29, vcc
	s_nop 1
	v_mov_b32_dpp v28, v26 row_half_mirror row_mask:0xf bank_mask:0xf bound_ctrl:1
	v_mov_b32_dpp v29, v27 row_half_mirror row_mask:0xf bank_mask:0xf bound_ctrl:1
	v_cmp_gt_u64_e32 vcc, v[28:29], v[26:27]
	s_nop 1
	v_cndmask_b32_e32 v26, v26, v28, vcc
	v_cndmask_b32_e32 v27, v27, v29, vcc
	v_cndmask_b32_e64 v34, v34, v26, s[2:3]
	v_cndmask_b32_e64 v35, v35, v27, s[2:3]
	v_cmp_eq_u64_e32 vcc, v[12:13], v[26:27]
	s_and_saveexec_b64 s[36:37], vcc
	v_mov_b64_e32 v[12:13], v[14:15]
	v_mov_b64_e32 v[14:15], v[16:17]
	v_mov_b64_e32 v[16:17], v[18:19]
	v_mov_b64_e32 v[18:19], v[20:21]
	v_mov_b64_e32 v[20:21], v[22:23]
	v_mov_b64_e32 v[22:23], v[24:25]
	v_mov_b64_e32 v[24:25], 0
	s_mov_b64 exec, s[36:37]
	v_mov_b32_dpp v28, v12 quad_perm:[1,0,3,2] row_mask:0xf bank_mask:0xf bound_ctrl:1
; #define ARGMAX_STEP(CTRL) { const float ov = dppf<CTRL>(best); const int oc = dppi<CTRL>(bc);                \
;           const bool take = ov > best || (ov == best && oc < bc); best = take ? ov : best; bc = take ? oc : bc; }
; static __device__ __forceinline__ void phase_peer(const Params& p, char* smraw) {
;     ...
;       for (int round = 0; round < 16; ++round) {
;         float best = cand[0]; int bc = ccode[0];
; #pragma unroll
;         for (int m = 1; m < 7; ++m) if (cand[m] > best) { best = cand[m]; bc = ccode[m]; }
;     ...
;         ARGMAX_STEP(0xB1) ARGMAX_STEP(0x4E) ARGMAX_STEP(0x141)
;     ...
; #pragma unroll
;         for (int m = 0; m < 7; ++m) cand[m] = ccode[m] == bc ? -3.0e38f : cand[m];
;         if (round == 0) vmax = best;
;         if ((round & 7) == g) { myv[round >> 3] = best; myc[round >> 3] = bc; }
;       }
	v_mov_b32_dpp v29, v13 quad_perm:[1,0,3,2] row_mask:0xf bank_mask:0xf bound_ctrl:1
	v_cmp_gt_u64_e32 vcc, v[28:29], v[12:13]
	s_nop 1
	v_cndmask_b32_e32 v26, v12, v28, vcc
	v_cndmask_b32_e32 v27, v13, v29, vcc
	s_nop 1
	v_mov_b32_dpp v28, v26 quad_perm:[2,3,0,1] row_mask:0xf bank_mask:0xf bound_ctrl:1
	v_mov_b32_dpp v29, v27 quad_perm:[2,3,0,1] row_mask:0xf bank_mask:0xf bound_ctrl:1
	v_cmp_gt_u64_e32 vcc, v[28:29], v[26:27]
	s_nop 1
	v_cndmask_b32_e32 v26, v26, v28, vcc
	v_cndmask_b32_e32 v27, v27, v29, vcc
	s_nop 1
	v_mov_b32_dpp v28, v26 row_half_mirror row_mask:0xf bank_mask:0xf bound_ctrl:1
	v_mov_b32_dpp v29, v27 row_half_mirror row_mask:0xf bank_mask:0xf bound_ctrl:1
	v_cmp_gt_u64_e32 vcc, v[28:29], v[26:27]
	s_nop 1
	v_cndmask_b32_e32 v26, v26, v28, vcc
	v_cndmask_b32_e32 v27, v27, v29, vcc
	v_cndmask_b32_e64 v34, v34, v26, s[4:5]
	v_cndmask_b32_e64 v35, v35, v27, s[4:5]
	v_cmp_eq_u64_e32 vcc, v[12:13], v[26:27]
	s_and_saveexec_b64 s[36:37], vcc
	v_mov_b64_e32 v[12:13], v[14:15]
	v_mov_b64_e32 v[14:15], v[16:17]
	v_mov_b64_e32 v[16:17], v[18:19]
	v_mov_b64_e32 v[18:19], v[20:21]
	v_mov_b64_e32 v[20:21], v[22:23]
	v_mov_b64_e32 v[22:23], v[24:25]
	v_mov_b64_e32 v[24:25], 0
	s_mov_b64 exec, s[36:37]
	v_mov_b32_dpp v28, v12 quad_perm:[1,0,3,2] row_mask:0xf bank_mask:0xf bound_ctrl:1
	v_mov_b32_dpp v29, v13 quad_perm:[1,0,3,2] row_mask:0xf bank_mask:0xf bound_ctrl:1
	v_cmp_gt_u64_e32 vcc, v[28:29], v[12:13]
	s_nop 1
	v_cndmask_b32_e32 v26, v12, v28, vcc
	v_cndmask_b32_e32 v27, v13, v29, vcc
	s_nop 1
	v_mov_b32_dpp v28, v26 quad_perm:[2,3,0,1] row_mask:0xf bank_mask:0xf bound_ctrl:1
	v_mov_b32_dpp v29, v27 quad_perm:[2,3,0,1] row_mask:0xf bank_mask:0xf bound_ctrl:1
	v_cmp_gt_u64_e32 vcc, v[28:29], v[26:27]
	s_nop 1
	v_cndmask_b32_e32 v26, v26, v28, vcc
	v_cndmask_b32_e32 v27, v27, v29, vcc
	s_nop 1
	v_mov_b32_dpp v28, v26 row_half_mirror row_mask:0xf bank_mask:0xf bound_ctrl:1
	v_mov_b32_dpp v29, v27 row_half_mirror row_mask:0xf bank_mask:0xf bound_ctrl:1
	v_cmp_gt_u64_e32 vcc, v[28:29], v[26:27]
	s_nop 1
	v_cndmask_b32_e32 v26, v26, v28, vcc
	v_cndmask_b32_e32 v27, v27, v29, vcc
	v_cndmask_b32_e64 v34, v34, v26, s[6:7]
	v_cndmask_b32_e64 v35, v35, v27, s[6:7]
	v_cmp_eq_u64_e32 vcc, v[12:13], v[26:27]
	s_and_saveexec_b64 s[36:37], vcc
	v_mov_b64_e32 v[12:13], v[14:15]
	v_mov_b64_e32 v[14:15], v[16:17]
	v_mov_b64_e32 v[16:17], v[18:19]
	v_mov_b64_e32 v[18:19], v[20:21]
	v_mov_b64_e32 v[20:21], v[22:23]
	v_mov_b64_e32 v[22:23], v[24:25]
	v_mov_b64_e32 v[24:25], 0
	s_mov_b64 exec, s[36:37]
	v_mov_b32_dpp v28, v12 quad_perm:[1,0,3,2] row_mask:0xf bank_mask:0xf bound_ctrl:1
	v_mov_b32_dpp v29, v13 quad_perm:[1,0,3,2] row_mask:0xf bank_mask:0xf bound_ctrl:1
	v_cmp_gt_u64_e32 vcc, v[28:29], v[12:13]
	s_nop 1
	v_cndmask_b32_e32 v26, v12, v28, vcc
	v_cndmask_b32_e32 v27, v13, v29, vcc
	s_nop 1
	v_mov_b32_dpp v28, v26 quad_perm:[2,3,0,1] row_mask:0xf bank_mask:0xf bound_ctrl:1
	v_mov_b32_dpp v29, v27 quad_perm:[2,3,0,1] row_mask:0xf bank_mask:0xf bound_ctrl:1
	v_cmp_gt_u64_e32 vcc, v[28:29], v[26:27]
	s_nop 1
	v_cndmask_b32_e32 v26, v26, v28, vcc
	v_cndmask_b32_e32 v27, v27, v29, vcc
	s_nop 1
	v_mov_b32_dpp v28, v26 row_half_mirror row_mask:0xf bank_mask:0xf bound_ctrl:1
	v_mov_b32_dpp v29, v27 row_half_mirror row_mask:0xf bank_mask:0xf bound_ctrl:1
	v_cmp_gt_u64_e32 vcc, v[28:29], v[26:27]
	s_nop 1
	v_cndmask_b32_e32 v26, v26, v28, vcc
	v_cndmask_b32_e32 v27, v27, v29, vcc
	v_cndmask_b32_e64 v34, v34, v26, s[8:9]
	v_cndmask_b32_e64 v35, v35, v27, s[8:9]
	v_cmp_eq_u64_e32 vcc, v[12:13], v[26:27]
	s_and_saveexec_b64 s[36:37], vcc
	v_mov_b64_e32 v[12:13], v[14:15]
	v_mov_b64_e32 v[14:15], v[16:17]
	v_mov_b64_e32 v[16:17], v[18:19]
	v_mov_b64_e32 v[18:19], v[20:21]
	v_mov_b64_e32 v[20:21], v[22:23]
	v_mov_b64_e32 v[22:23], v[24:25]
	v_mov_b64_e32 v[24:25], 0
	s_mov_b64 exec, s[36:37]
	v_mov_b32_dpp v28, v12 quad_perm:[1,0,3,2] row_mask:0xf bank_mask:0xf bound_ctrl:1
	v_mov_b32_dpp v29, v13 quad_perm:[1,0,3,2] row_mask:0xf bank_mask:0xf bound_ctrl:1
	v_cmp_gt_u64_e32 vcc, v[28:29], v[12:13]
	s_nop 1
	v_cndmask_b32_e32 v26, v12, v28, vcc
	v_cndmask_b32_e32 v27, v13, v29, vcc
	s_nop 1
	v_mov_b32_dpp v28, v26 quad_perm:[2,3,0,1] row_mask:0xf bank_mask:0xf bound_ctrl:1
	v_mov_b32_dpp v29, v27 quad_perm:[2,3,0,1] row_mask:0xf bank_mask:0xf bound_ctrl:1
	v_cmp_gt_u64_e32 vcc, v[28:29], v[26:27]
	s_nop 1
	v_cndmask_b32_e32 v26, v26, v28, vcc
	v_cndmask_b32_e32 v27, v27, v29, vcc
	s_nop 1
	v_mov_b32_dpp v28, v26 row_half_mirror row_mask:0xf bank_mask:0xf bound_ctrl:1
	v_mov_b32_dpp v29, v27 row_half_mirror row_mask:0xf bank_mask:0xf bound_ctrl:1
	v_cmp_gt_u64_e32 vcc, v[28:29], v[26:27]
	s_nop 1
	v_cndmask_b32_e32 v26, v26, v28, vcc
	v_cndmask_b32_e32 v27, v27, v29, vcc
	v_cndmask_b32_e64 v34, v34, v26, s[10:11]
	v_cndmask_b32_e64 v35, v35, v27, s[10:11]
	v_cmp_eq_u64_e32 vcc, v[12:13], v[26:27]
	s_and_saveexec_b64 s[36:37], vcc
	v_mov_b64_e32 v[12:13], v[14:15]
	v_mov_b64_e32 v[14:15], v[16:17]
	v_mov_b64_e32 v[16:17], v[18:19]
	v_mov_b64_e32 v[18:19], v[20:21]
	v_mov_b64_e32 v[20:21], v[22:23]
	v_mov_b64_e32 v[22:23], v[24:25]
	v_mov_b64_e32 v[24:25], 0
	s_mov_b64 exec, s[36:37]
	v_mov_b32_dpp v28, v12 quad_perm:[1,0,3,2] row_mask:0xf bank_mask:0xf bound_ctrl:1
	v_mov_b32_dpp v29, v13 quad_perm:[1,0,3,2] row_mask:0xf bank_mask:0xf bound_ctrl:1
	v_cmp_gt_u64_e32 vcc, v[28:29], v[12:13]
	s_nop 1
	v_cndmask_b32_e32 v26, v12, v28, vcc
	v_cndmask_b32_e32 v27, v13, v29, vcc
	s_nop 1
	v_mov_b32_dpp v28, v26 quad_perm:[2,3,0,1] row_mask:0xf bank_mask:0xf bound_ctrl:1
	v_mov_b32_dpp v29, v27 quad_perm:[2,3,0,1] row_mask:0xf bank_mask:0xf bound_ctrl:1
; #define ARGMAX_STEP(CTRL) { const float ov = dppf<CTRL>(best); const int oc = dppi<CTRL>(bc);                \
;           const bool take = ov > best || (ov == best && oc < bc); best = take ? ov : best; bc = take ? oc : bc; }
; static __device__ __forceinline__ void phase_peer(const Params& p, char* smraw) {
;     ...
;       for (int round = 0; round < 16; ++round) {
;         float best = cand[0]; int bc = ccode[0];
; #pragma unroll
;         for (int m = 1; m < 7; ++m) if (cand[m] > best) { best = cand[m]; bc = ccode[m]; }
;     ...
;         ARGMAX_STEP(0xB1) ARGMAX_STEP(0x4E) ARGMAX_STEP(0x141)
;     ...
; #pragma unroll
;         for (int m = 0; m < 7; ++m) cand[m] = ccode[m] == bc ? -3.0e38f : cand[m];
;         if (round == 0) vmax = best;
;         if ((round & 7) == g) { myv[round >> 3] = best; myc[round >> 3] = bc; }
;       }
;       const float e0 = __expf(myv[0] - vmax), e1 = __expf(myv[1] - vmax);
;       float se = e0 + e1;
;       se += dppf<0xB1>(se); se += dppf<0x4E>(se); se += dppf<0x141>(se);
;       const float inv = 1.f / se;
;       const unsigned char* tip = TI + ((size_t)t * 16 + head * 2) * 16;
; #pragma unroll
;       for (int s = 0; s < 2; ++s) {
;         const int i0 = tip[myc[s] >> 4], i1 = tip[16 + (myc[s] & 15)];
;         sIdx[head * 16 + g + 8 * s] = i0 * 128 + i1;
;         sGate[head * 16 + g + 8 * s] = (s ? e1 : e0) * inv;
;       }
	v_cmp_gt_u64_e32 vcc, v[28:29], v[26:27]
	s_nop 1
	v_cndmask_b32_e32 v26, v26, v28, vcc
	v_cndmask_b32_e32 v27, v27, v29, vcc
	s_nop 1
	v_mov_b32_dpp v28, v26 row_half_mirror row_mask:0xf bank_mask:0xf bound_ctrl:1
	v_mov_b32_dpp v29, v27 row_half_mirror row_mask:0xf bank_mask:0xf bound_ctrl:1
	v_cmp_gt_u64_e32 vcc, v[28:29], v[26:27]
	s_nop 1
	v_cndmask_b32_e32 v26, v26, v28, vcc
	v_cndmask_b32_e32 v27, v27, v29, vcc
	v_cndmask_b32_e64 v34, v34, v26, s[12:13]
	v_cndmask_b32_e64 v35, v35, v27, s[12:13]
	v_cmp_eq_u64_e32 vcc, v[12:13], v[26:27]
	s_and_saveexec_b64 s[36:37], vcc
	v_mov_b64_e32 v[12:13], v[14:15]
	v_mov_b64_e32 v[14:15], v[16:17]
	v_mov_b64_e32 v[16:17], v[18:19]
	v_mov_b64_e32 v[18:19], v[20:21]
	v_mov_b64_e32 v[20:21], v[22:23]
	v_mov_b64_e32 v[22:23], v[24:25]
	v_mov_b64_e32 v[24:25], 0
	s_mov_b64 exec, s[36:37]
	v_mov_b32_dpp v28, v12 quad_perm:[1,0,3,2] row_mask:0xf bank_mask:0xf bound_ctrl:1
	v_mov_b32_dpp v29, v13 quad_perm:[1,0,3,2] row_mask:0xf bank_mask:0xf bound_ctrl:1
	v_cmp_gt_u64_e32 vcc, v[28:29], v[12:13]
	s_nop 1
	v_cndmask_b32_e32 v26, v12, v28, vcc
	v_cndmask_b32_e32 v27, v13, v29, vcc
	s_nop 1
	v_mov_b32_dpp v28, v26 quad_perm:[2,3,0,1] row_mask:0xf bank_mask:0xf bound_ctrl:1
	v_mov_b32_dpp v29, v27 quad_perm:[2,3,0,1] row_mask:0xf bank_mask:0xf bound_ctrl:1
	v_cmp_gt_u64_e32 vcc, v[28:29], v[26:27]
	s_nop 1
	v_cndmask_b32_e32 v26, v26, v28, vcc
	v_cndmask_b32_e32 v27, v27, v29, vcc
	s_nop 1
	v_mov_b32_dpp v28, v26 row_half_mirror row_mask:0xf bank_mask:0xf bound_ctrl:1
	v_mov_b32_dpp v29, v27 row_half_mirror row_mask:0xf bank_mask:0xf bound_ctrl:1
	v_cmp_gt_u64_e32 vcc, v[28:29], v[26:27]
	s_nop 1
	v_cndmask_b32_e32 v26, v26, v28, vcc
	v_cndmask_b32_e32 v27, v27, v29, vcc
	v_cndmask_b32_e64 v34, v34, v26, s[14:15]
	v_cndmask_b32_e64 v35, v35, v27, s[14:15]
	v_cmp_eq_u64_e32 vcc, v[12:13], v[26:27]
	s_and_saveexec_b64 s[36:37], vcc
	v_mov_b64_e32 v[12:13], v[14:15]
	v_mov_b64_e32 v[14:15], v[16:17]
	v_mov_b64_e32 v[16:17], v[18:19]
	v_mov_b64_e32 v[18:19], v[20:21]
	v_mov_b64_e32 v[20:21], v[22:23]
	v_mov_b64_e32 v[22:23], v[24:25]
	v_mov_b64_e32 v[24:25], 0
	s_mov_b64 exec, s[36:37]
	v_mov_b32_dpp v28, v12 quad_perm:[1,0,3,2] row_mask:0xf bank_mask:0xf bound_ctrl:1
	v_mov_b32_dpp v29, v13 quad_perm:[1,0,3,2] row_mask:0xf bank_mask:0xf bound_ctrl:1
	v_cmp_gt_u64_e32 vcc, v[28:29], v[12:13]
	s_nop 1
	v_cndmask_b32_e32 v26, v12, v28, vcc
	v_cndmask_b32_e32 v27, v13, v29, vcc
	s_nop 1
	v_mov_b32_dpp v28, v26 quad_perm:[2,3,0,1] row_mask:0xf bank_mask:0xf bound_ctrl:1
	v_mov_b32_dpp v29, v27 quad_perm:[2,3,0,1] row_mask:0xf bank_mask:0xf bound_ctrl:1
	v_cmp_gt_u64_e32 vcc, v[28:29], v[26:27]
	s_nop 1
	v_cndmask_b32_e32 v26, v26, v28, vcc
	v_cndmask_b32_e32 v27, v27, v29, vcc
	s_nop 1
	v_mov_b32_dpp v28, v26 row_half_mirror row_mask:0xf bank_mask:0xf bound_ctrl:1
	v_mov_b32_dpp v29, v27 row_half_mirror row_mask:0xf bank_mask:0xf bound_ctrl:1
	v_cmp_gt_u64_e32 vcc, v[28:29], v[26:27]
	s_nop 1
	v_cndmask_b32_e32 v26, v26, v28, vcc
	v_cndmask_b32_e32 v27, v27, v29, vcc
	v_cndmask_b32_e64 v34, v34, v26, s[16:17]
	v_cndmask_b32_e64 v35, v35, v27, s[16:17]
	v_sub_u32_e32 v6, 0xff, v32
	v_sub_u32_e32 v9, 0xff, v34
	v_ashrrev_i32_e32 v30, 31, v33
	v_not_b32_e32 v30, v30
	v_or_b32_e32 v30, 0x80000000, v30
	v_xor_b32_e32 v3, v33, v30
	v_ashrrev_i32_e32 v30, 31, v35
	v_not_b32_e32 v30, v30
	v_or_b32_e32 v30, 0x80000000, v30
	v_xor_b32_e32 v13, v35, v30
	v_ashrrev_i32_e32 v30, 31, v38
	v_not_b32_e32 v30, v30
	v_or_b32_e32 v30, 0x80000000, v30
	v_xor_b32_e32 v2, v38, v30
	v_lshl_add_u64 v[0:1], s[46:47], 0, v[0:1]
	v_ashrrev_i32_e32 v24, 4, v6
	v_and_b32_e32 v58, 15, v6
	v_ashrrev_i32_e32 v52, 4, v9
	v_ashrrev_i32_e32 v25, 31, v24
	v_lshl_add_u64 v[50:51], v[0:1], 0, v[58:59]
	v_ashrrev_i32_e32 v53, 31, v52
	v_and_b32_e32 v58, 15, v9
	v_lshl_add_u64 v[24:25], v[0:1], 0, v[24:25]
	v_lshl_add_u64 v[52:53], v[0:1], 0, v[52:53]
	v_lshl_add_u64 v[0:1], v[0:1], 0, v[58:59]
	global_load_ubyte v6, v[24:25], off
	global_load_ubyte v9, v[50:51], off offset:16
	global_load_ubyte v12, v[52:53], off
	s_nop 0
	global_load_ubyte v0, v[0:1], off offset:16
	v_mov_b32_e32 v1, v13
	v_sub_f32_e32 v3, v3, v2
	v_sub_f32_e32 v1, v1, v2
	v_mul_f32_e32 v3, 0x3fb8aa3b, v3
	v_mul_f32_e32 v1, 0x3fb8aa3b, v1
	v_exp_f32_e32 v3, v3
	v_exp_f32_e32 v1, v1
	v_lshlrev_b64 v[100:101], 10, v[56:57]
	s_mov_b32 s52, 0
	v_mov_b32_e32 v77, v200
	v_add_f32_e32 v2, v3, v1
	s_waitcnt vmcnt(0)
	v_lshl_add_u32 v0, v12, 7, v0
	v_add_f32_dpp v2, v2, v2 quad_perm:[1,0,3,2] row_mask:0xf bank_mask:0xf bound_ctrl:1
	s_nop 1
	v_add_f32_dpp v2, v2, v2 quad_perm:[2,3,0,1] row_mask:0xf bank_mask:0xf bound_ctrl:1
	s_nop 1
	v_add_f32_dpp v2, v2, v2 row_half_mirror row_mask:0xf bank_mask:0xf bound_ctrl:1
	v_div_scale_f32 v4, s[36:37], v2, v2, 1.0
	v_rcp_f32_e32 v5, v4
	v_div_scale_f32 v7, vcc, 1.0, v2, 1.0
	v_fma_f32 v8, -v4, v5, 1.0
	v_fmac_f32_e32 v5, v8, v5
	v_mul_f32_e32 v8, v7, v5
	v_fma_f32 v10, -v4, v8, v7
	v_fmac_f32_e32 v8, v10, v5
	v_fma_f32 v4, -v4, v8, v7
	v_div_fmas_f32 v4, v4, v5, v8
	v_div_fixup_f32 v2, v4, v2, 1.0
	v_mul_f32_e32 v3, v3, v2
	v_mul_f32_e32 v1, v1, v2
	v_lshl_add_u32 v2, v6, 7, v9
	ds_write2_b32 v187, v2, v0 offset1:8
	ds_write2_b32 v187, v3, v1 offset0:128 offset1:136
	v_lshlrev_b64 v[0:1], 11, v[56:57]
	v_lshl_add_u64 v[102:103], v[62:63], 0, v[0:1]
	s_waitcnt lgkmcnt(0)
; __device__ __forceinline__ float bflo(unsigned u) { return __uint_as_float(u << 16); }
; __device__ __forceinline__ float bfhi(unsigned u) { return __uint_as_float(u & 0xffff0000u); }
; static __device__ __forceinline__ void phase_peer(const Params& p, char* smraw) {
;     ...
;     f2_t z2[32];
;     {
;       const u16* xbh = X1B + (size_t)t * 1024 + sub * 32;
; #pragma unroll
;       for (int j = 0; j < 2; ++j)
; #pragma unroll
;         for (int q4 = 0; q4 < 4; ++q4) {
;           const u32x4 wv = *(const u32x4*)(xbh + j * 512 + q4 * 8);
; #pragma unroll
;           for (int e = 0; e < 4; ++e) z2[j * 16 + 4 * q4 + e] = f2_t{bflo(wv[e]) * rs, bfhi(wv[e]) * rs};
;         }
;     }
;     {
;       u32x4 ua[2], ub[2], uc[2], ud[2]; int ea, eb, ec, ed; float ga_, gb2, gc, gd, sua, sub_, suc, sud, sva, svb, svc, svd;
;     ...
;       GLOADU(ua, sua, sva, ea, ga_, 0); GLOADU(ub, sub_, svb, eb, gb2, 1); GLOADU(uc, suc, svc, ec, gc, 2);
	global_load_dwordx4 v[40:43], v[102:103], off
	global_load_dwordx4 v[32:35], v[102:103], off offset:16
	global_load_dwordx4 v[28:31], v[102:103], off offset:32
	global_load_dwordx4 v[24:27], v[102:103], off offset:48
	ds_read2_b32 v[0:1], v186 offset1:4
	global_load_dwordx4 v[146:149], v[102:103], off offset:1072
	global_load_dwordx4 v[136:139], v[102:103], off offset:1056
	global_load_dwordx4 v[128:131], v[102:103], off offset:1040
	global_load_dwordx4 v[120:123], v[102:103], off offset:1024
	ds_read2_b32 v[38:39], v186 offset0:8 offset1:128
	s_waitcnt lgkmcnt(1)
	v_ashrrev_i32_e32 v3, 31, v0
	v_mov_b32_e32 v2, v0
	v_ashrrev_i32_e32 v5, 31, v1
	v_mov_b32_e32 v4, v1
	s_waitcnt lgkmcnt(0)
	v_ashrrev_i32_e32 v1, 31, v38
	v_mov_b32_e32 v0, v38
	v_lshlrev_b64 v[6:7], 9, v[2:3]
	v_lshlrev_b64 v[2:3], 2, v[2:3]
	v_lshlrev_b64 v[8:9], 9, v[4:5]
	v_lshlrev_b64 v[4:5], 2, v[4:5]
	v_lshlrev_b64 v[10:11], 9, v[0:1]
	v_lshlrev_b64 v[0:1], 2, v[0:1]
	v_lshl_add_u64 v[6:7], v[64:65], 0, v[6:7]
	v_lshl_add_u64 v[12:13], s[38:39], 0, v[2:3]
	v_lshl_add_u64 v[14:15], s[40:41], 0, v[2:3]
	v_lshl_add_u64 v[16:17], v[64:65], 0, v[8:9]
	v_lshl_add_u64 v[18:19], s[38:39], 0, v[4:5]
	v_lshl_add_u64 v[20:21], s[40:41], 0, v[4:5]
	v_lshl_add_u64 v[22:23], v[64:65], 0, v[10:11]
	v_lshl_add_u64 v[44:45], s[38:39], 0, v[0:1]
	v_lshl_add_u64 v[46:47], s[40:41], 0, v[0:1]
	global_load_dwordx4 v[0:3], v[6:7], off
	s_nop 0
	global_load_dwordx4 v[4:7], v[6:7], off offset:256
	s_nop 0
	global_load_dword v38, v[12:13], off
	global_load_dword v57, v[14:15], off
	global_load_dwordx4 v[8:11], v[16:17], off
	s_nop 0
	global_load_dwordx4 v[12:15], v[16:17], off offset:256
	global_load_dword v58, v[18:19], off
	global_load_dword v71, v[20:21], off
	s_nop 0
	global_load_dwordx4 v[16:19], v[22:23], off
	s_nop 0
	global_load_dwordx4 v[20:23], v[22:23], off offset:256
	s_nop 0
	global_load_dword v73, v[44:45], off
	global_load_dword v75, v[46:47], off
	s_waitcnt vmcnt(19)
	v_lshlrev_b32_e32 v44, 16, v40
	v_and_b32_e32 v45, 0xffff0000, v40
	v_lshlrev_b32_e32 v40, 16, v41
	v_and_b32_e32 v41, 0xffff0000, v41
	v_lshlrev_b32_e32 v46, 16, v42
	v_and_b32_e32 v47, 0xffff0000, v42
	s_waitcnt vmcnt(18)
	v_lshlrev_b32_e32 v50, 16, v33
	v_and_b32_e32 v51, 0xffff0000, v33
	v_lshlrev_b32_e32 v54, 16, v35
	v_and_b32_e32 v55, 0xffff0000, v35
	s_waitcnt vmcnt(17)
	v_lshlrev_b32_e32 v104, 16, v28
	v_and_b32_e32 v105, 0xffff0000, v28
	v_lshlrev_b32_e32 v28, 16, v29
	v_and_b32_e32 v29, 0xffff0000, v29
	v_lshlrev_b32_e32 v48, 16, v32
	v_and_b32_e32 v49, 0xffff0000, v32
	v_lshlrev_b32_e32 v52, 16, v34
	v_and_b32_e32 v53, 0xffff0000, v34
	v_lshlrev_b32_e32 v106, 16, v30
	v_and_b32_e32 v107, 0xffff0000, v30
	v_pk_mul_f32 v[34:35], v[36:37], v[40:41] op_sel_hi:[0,1]
	v_pk_mul_f32 v[40:41], v[36:37], v[46:47] op_sel_hi:[0,1]
	v_pk_mul_f32 v[46:47], v[36:37], v[50:51] op_sel_hi:[0,1]
	v_pk_mul_f32 v[50:51], v[36:37], v[54:55] op_sel_hi:[0,1]
	v_pk_mul_f32 v[54:55], v[36:37], v[28:29] op_sel_hi:[0,1]
	v_lshlrev_b32_e32 v28, 16, v31
	v_and_b32_e32 v29, 0xffff0000, v31
	v_pk_mul_f32 v[32:33], v[36:37], v[44:45] op_sel_hi:[0,1]
	v_pk_mul_f32 v[44:45], v[36:37], v[48:49] op_sel_hi:[0,1]
	v_pk_mul_f32 v[48:49], v[36:37], v[52:53] op_sel_hi:[0,1]
	v_pk_mul_f32 v[52:53], v[36:37], v[104:105] op_sel_hi:[0,1]
	v_pk_mul_f32 v[104:105], v[36:37], v[106:107] op_sel_hi:[0,1]
	v_pk_mul_f32 v[106:107], v[36:37], v[28:29] op_sel_hi:[0,1]
	s_waitcnt vmcnt(16)
	v_lshlrev_b32_e32 v28, 16, v24
	v_and_b32_e32 v29, 0xffff0000, v24
	v_lshlrev_b32_e32 v24, 16, v25
	v_and_b32_e32 v25, 0xffff0000, v25
	v_pk_mul_f32 v[110:111], v[36:37], v[24:25] op_sel_hi:[0,1]
	v_lshlrev_b32_e32 v24, 16, v26
	v_and_b32_e32 v25, 0xffff0000, v26
	v_pk_mul_f32 v[112:113], v[36:37], v[24:25] op_sel_hi:[0,1]
	v_lshlrev_b32_e32 v24, 16, v27
	v_and_b32_e32 v25, 0xffff0000, v27
	v_pk_mul_f32 v[114:115], v[36:37], v[24:25] op_sel_hi:[0,1]
	s_waitcnt vmcnt(12)
	v_lshlrev_b32_e32 v24, 16, v120
	v_and_b32_e32 v25, 0xffff0000, v120
	v_pk_mul_f32 v[116:117], v[36:37], v[24:25] op_sel_hi:[0,1]
	v_lshlrev_b32_e32 v24, 16, v121
	v_and_b32_e32 v25, 0xffff0000, v121
	v_pk_mul_f32 v[118:119], v[36:37], v[24:25] op_sel_hi:[0,1]
	v_lshlrev_b32_e32 v24, 16, v122
	v_and_b32_e32 v25, 0xffff0000, v122
	v_pk_mul_f32 v[120:121], v[36:37], v[24:25] op_sel_hi:[0,1]
	v_lshlrev_b32_e32 v24, 16, v123
	v_and_b32_e32 v25, 0xffff0000, v123
	v_pk_mul_f32 v[122:123], v[36:37], v[24:25] op_sel_hi:[0,1]
	v_lshlrev_b32_e32 v24, 16, v128
	v_and_b32_e32 v25, 0xffff0000, v128
	v_pk_mul_f32 v[124:125], v[36:37], v[24:25] op_sel_hi:[0,1]
	v_lshlrev_b32_e32 v24, 16, v129
	v_and_b32_e32 v25, 0xffff0000, v129
	v_pk_mul_f32 v[126:127], v[36:37], v[24:25] op_sel_hi:[0,1]
	v_lshlrev_b32_e32 v24, 16, v130
	v_and_b32_e32 v25, 0xffff0000, v130
	v_pk_mul_f32 v[128:129], v[36:37], v[24:25] op_sel_hi:[0,1]
	v_lshlrev_b32_e32 v24, 16, v131
	v_and_b32_e32 v25, 0xffff0000, v131
	v_pk_mul_f32 v[130:131], v[36:37], v[24:25] op_sel_hi:[0,1]
	v_lshlrev_b32_e32 v24, 16, v136
	v_and_b32_e32 v25, 0xffff0000, v136
	v_pk_mul_f32 v[132:133], v[36:37], v[24:25] op_sel_hi:[0,1]
	v_lshlrev_b32_e32 v24, 16, v137
	v_and_b32_e32 v25, 0xffff0000, v137
	v_pk_mul_f32 v[134:135], v[36:37], v[24:25] op_sel_hi:[0,1]
	v_lshlrev_b32_e32 v24, 16, v138
	v_and_b32_e32 v25, 0xffff0000, v138
	v_pk_mul_f32 v[136:137], v[36:37], v[24:25] op_sel_hi:[0,1]
	v_lshlrev_b32_e32 v24, 16, v139
	v_and_b32_e32 v25, 0xffff0000, v139
	v_pk_mul_f32 v[138:139], v[36:37], v[24:25] op_sel_hi:[0,1]
	v_lshlrev_b32_e32 v24, 16, v146
	v_and_b32_e32 v25, 0xffff0000, v146
	v_pk_mul_f32 v[140:141], v[36:37], v[24:25] op_sel_hi:[0,1]
	v_lshlrev_b32_e32 v24, 16, v147
	v_and_b32_e32 v25, 0xffff0000, v147
	ds_read2_b32 v[146:147], v186 offset0:132 offset1:136
	v_pk_mul_f32 v[142:143], v[36:37], v[24:25] op_sel_hi:[0,1]
	v_lshlrev_b32_e32 v24, 16, v148
	v_and_b32_e32 v25, 0xffff0000, v148
	v_lshlrev_b32_e32 v42, 16, v43
	v_and_b32_e32 v43, 0xffff0000, v43
	v_pk_mul_f32 v[144:145], v[36:37], v[24:25] op_sel_hi:[0,1]
	v_lshlrev_b32_e32 v24, 16, v149
	v_and_b32_e32 v25, 0xffff0000, v149
	v_pk_mul_f32 v[42:43], v[36:37], v[42:43] op_sel_hi:[0,1]
	v_pk_mul_f32 v[108:109], v[36:37], v[28:29] op_sel_hi:[0,1]
	v_pk_mul_f32 v[36:37], v[36:37], v[24:25] op_sel_hi:[0,1]
	s_waitcnt lgkmcnt(0)
	v_mov_b32_e32 v149, v146
	s_branch .LBB0_864

; __device__ __forceinline__ float bflo(unsigned u) { return __uint_as_float(u << 16); }
; __device__ __forceinline__ float bfhi(unsigned u) { return __uint_as_float(u & 0xffff0000u); }
; static __device__ __forceinline__ void phase_peer(const Params& p, char* smraw) {
;     ...
;     __builtin_amdgcn_wave_barrier();
;     float ss = 0.f;
;     const u16* xb2 = X1B + (size_t)t * 1024 + sub * 32;
; #pragma unroll
;     for (int j = 0; j < 2; ++j)
; #pragma unroll
;       for (int q = 0; q < 8; ++q) {
;         const u32x2 aw = *(const u32x2*)(xb2 + j * 512 + q * 4);
;         const float4 a = {bflo(aw[0]), bfhi(aw[0]), bflo(aw[1]), bfhi(aw[1])};
;         float o0 = o2[j * 16 + 2 * q][0], o1 = o2[j * 16 + 2 * q][1], o2_ = o2[j * 16 + 2 * q + 1][0], o3 = o2[j * 16 + 2 * q + 1][1];
;         o0 = sum_x16_x32(o0); o1 = sum_x16_x32(o1); o2_ = sum_x16_x32(o2_); o3 = sum_x16_x32(o3);
;         o0 += a.x; o1 += a.y; o2_ += a.z; o3 += a.w;
;         ss += (o0 * o0 + o1 * o1) + (o2_ * o2_ + o3 * o3);
;         o2[j * 16 + 2 * q] = f2_t{o0, o1}; o2[j * 16 + 2 * q + 1] = f2_t{o2_, o3};
;       }
;     ss = sum16(ss);
;     const float rs2 = rsqrtf(ss * (1.f / 1024.f) + EPS);
.LBB0_902:
	v_lshrrev_b32_e32 v24, 1, v185
	v_and_b32_e32 v25, 1, v185
	v_lshlrev_b32_e32 v24, 11, v24
	v_lshl_or_b32 v24, v25, 6, v24
	v_mov_b32_e32 v25, 0
	v_lshrrev_b32_e32 v26, 1, v24
	v_mov_b32_e32 v27, 0
	v_lshl_add_u64 v[28:29], v[102:103], 0, v[26:27]
	v_lshl_add_u64 v[30:31], v[68:69], 0, v[24:25]
	global_load_dwordx4 v[0:3], v[28:29], off
	global_load_dwordx4 v[4:7], v[28:29], off offset:16
	global_load_dwordx4 v[8:11], v[30:31], off
	global_load_dwordx4 v[12:15], v[30:31], off offset:16
	global_load_dwordx4 v[16:19], v[30:31], off offset:32
	global_load_dwordx4 v[20:23], v[30:31], off offset:48
	v_lshl_add_u64 v[32:33], v[100:101], 2, s[58:59]
	v_mov_b32_e32 v99, v59
	v_lshl_add_u64 v[32:33], v[32:33], 0, v[98:99]
	v_lshl_add_u64 v[32:33], v[32:33], 0, v[24:25]
	v_permlane16_swap_b32_e32 v166, v150
	v_permlane16_swap_b32_e32 v167, v151
	v_permlane16_swap_b32_e32 v164, v148
	v_permlane16_swap_b32_e32 v165, v149
	v_permlane16_swap_b32_e32 v162, v146
	v_permlane16_swap_b32_e32 v163, v147
	v_permlane16_swap_b32_e32 v160, v144
	v_permlane16_swap_b32_e32 v161, v145
	v_permlane16_swap_b32_e32 v158, v142
	v_permlane16_swap_b32_e32 v159, v143
	v_permlane16_swap_b32_e32 v156, v140
	v_permlane16_swap_b32_e32 v157, v141
	v_permlane16_swap_b32_e32 v154, v138
	v_permlane16_swap_b32_e32 v155, v139
	v_permlane16_swap_b32_e32 v152, v136
	v_permlane16_swap_b32_e32 v153, v137
	v_permlane16_swap_b32_e32 v134, v118
	v_permlane16_swap_b32_e32 v135, v119
	v_permlane16_swap_b32_e32 v132, v116
	v_permlane16_swap_b32_e32 v133, v117
	v_permlane16_swap_b32_e32 v130, v114
	v_permlane16_swap_b32_e32 v131, v115
	v_permlane16_swap_b32_e32 v128, v112
	v_permlane16_swap_b32_e32 v129, v113
	v_permlane16_swap_b32_e32 v126, v110
	v_permlane16_swap_b32_e32 v127, v111
	v_permlane16_swap_b32_e32 v124, v108
	v_permlane16_swap_b32_e32 v125, v109
	v_permlane16_swap_b32_e32 v122, v106
	v_permlane16_swap_b32_e32 v123, v107
	v_permlane16_swap_b32_e32 v120, v104
	v_permlane16_swap_b32_e32 v121, v105
	v_add_f32_e32 v166, v166, v150
	v_add_f32_e32 v167, v167, v151
	v_add_f32_e32 v164, v164, v148
	v_add_f32_e32 v165, v165, v149
	v_add_f32_e32 v162, v162, v146
	v_add_f32_e32 v163, v163, v147
	v_add_f32_e32 v160, v160, v144
	v_add_f32_e32 v161, v161, v145
	v_add_f32_e32 v158, v158, v142
	v_add_f32_e32 v159, v159, v143
	v_add_f32_e32 v156, v156, v140
	v_add_f32_e32 v157, v157, v141
	v_add_f32_e32 v154, v154, v138
	v_add_f32_e32 v155, v155, v139
	v_add_f32_e32 v152, v152, v136
	v_add_f32_e32 v153, v153, v137
	v_add_f32_e32 v134, v134, v118
	v_add_f32_e32 v135, v135, v119
	v_add_f32_e32 v132, v132, v116
	v_add_f32_e32 v133, v133, v117
	v_add_f32_e32 v130, v130, v114
	v_add_f32_e32 v131, v131, v115
	v_add_f32_e32 v128, v128, v112
	v_add_f32_e32 v129, v129, v113
	v_add_f32_e32 v126, v126, v110
	v_add_f32_e32 v127, v127, v111
	v_add_f32_e32 v124, v124, v108
	v_add_f32_e32 v125, v125, v109
	v_add_f32_e32 v122, v122, v106
	v_add_f32_e32 v123, v123, v107
	v_add_f32_e32 v120, v120, v104
	v_add_f32_e32 v121, v121, v105
	v_permlane32_swap_b32_e32 v166, v134
	v_permlane32_swap_b32_e32 v167, v135
	v_permlane32_swap_b32_e32 v164, v132
	v_permlane32_swap_b32_e32 v165, v133
	v_permlane32_swap_b32_e32 v162, v130
	v_permlane32_swap_b32_e32 v163, v131
	v_permlane32_swap_b32_e32 v160, v128
	v_permlane32_swap_b32_e32 v161, v129
	v_permlane32_swap_b32_e32 v158, v126
	v_permlane32_swap_b32_e32 v159, v127
	v_permlane32_swap_b32_e32 v156, v124
	v_permlane32_swap_b32_e32 v157, v125
	v_permlane32_swap_b32_e32 v154, v122
	v_permlane32_swap_b32_e32 v155, v123
	v_permlane32_swap_b32_e32 v152, v120
	v_permlane32_swap_b32_e32 v153, v121
	v_add_f32_e32 v166, v166, v134
	v_add_f32_e32 v167, v167, v135
	v_add_f32_e32 v164, v164, v132
	v_add_f32_e32 v165, v165, v133
	v_add_f32_e32 v162, v162, v130
	v_add_f32_e32 v163, v163, v131
	v_add_f32_e32 v160, v160, v128
	v_add_f32_e32 v161, v161, v129
	v_add_f32_e32 v158, v158, v126
	v_add_f32_e32 v159, v159, v127
	v_add_f32_e32 v156, v156, v124
	v_add_f32_e32 v157, v157, v125
	v_add_f32_e32 v154, v154, v122
	v_add_f32_e32 v155, v155, v123
	v_add_f32_e32 v152, v152, v120
	v_add_f32_e32 v153, v153, v121
	s_waitcnt vmcnt(4)
; __device__ __forceinline__ float bflo(unsigned u) { return __uint_as_float(u << 16); }
; __device__ __forceinline__ float bfhi(unsigned u) { return __uint_as_float(u & 0xffff0000u); }
; static __device__ __forceinline__ void phase_peer(const Params& p, char* smraw) {
;     ...
;     float ss = 0.f;
;     const u16* xb2 = X1B + (size_t)t * 1024 + sub * 32;
; #pragma unroll
;     for (int j = 0; j < 2; ++j)
; #pragma unroll
;       for (int q = 0; q < 8; ++q) {
;         const u32x2 aw = *(const u32x2*)(xb2 + j * 512 + q * 4);
;         const float4 a = {bflo(aw[0]), bfhi(aw[0]), bflo(aw[1]), bfhi(aw[1])};
;         float o0 = o2[j * 16 + 2 * q][0], o1 = o2[j * 16 + 2 * q][1], o2_ = o2[j * 16 + 2 * q + 1][0], o3 = o2[j * 16 + 2 * q + 1][1];
;         o0 = sum_x16_x32(o0); o1 = sum_x16_x32(o1); o2_ = sum_x16_x32(o2_); o3 = sum_x16_x32(o3);
;         o0 += a.x; o1 += a.y; o2_ += a.z; o3 += a.w;
;         ss += (o0 * o0 + o1 * o1) + (o2_ * o2_ + o3 * o3);
;         o2[j * 16 + 2 * q] = f2_t{o0, o1}; o2[j * 16 + 2 * q + 1] = f2_t{o2_, o3};
;       }
;     ss = sum16(ss);
;     const float rs2 = rsqrtf(ss * (1.f / 1024.f) + EPS);
; #pragma unroll
;     for (int j = 0; j < 2; ++j)
; #pragma unroll
;       for (int hq = 0; hq < 2; ++hq) {
;         if (j * 2 + hq == grp) {
; #pragma unroll
;           for (int q4 = 0; q4 < 4; ++q4) {
;             const int q = hq * 4 + q4;
;             const int c = sub * 32 + j * 512 + q * 4;
;             const float4 g = *(const float4*)(p.norm_final + c);
;             float4 o = {o2[j * 16 + 2 * q][0] * rs2 * g.x, o2[j * 16 + 2 * q][1] * rs2 * g.y,
;                         o2[j * 16 + 2 * q + 1][0] * rs2 * g.z, o2[j * 16 + 2 * q + 1][1] * rs2 * g.w};
;             *(float4*)(Y + (size_t)t * 1024 + c) = o;
;           }
;         }
;       }
	v_lshlrev_b32_e32 v34, 16, v0
	v_and_b32_e32 v35, 0xffff0000, v0
	v_pk_add_f32 v[166:167], v[166:167], v[34:35]
	v_lshlrev_b32_e32 v34, 16, v1
	v_and_b32_e32 v35, 0xffff0000, v1
	v_pk_add_f32 v[164:165], v[164:165], v[34:35]
	v_lshlrev_b32_e32 v34, 16, v2
	v_and_b32_e32 v35, 0xffff0000, v2
	v_pk_add_f32 v[162:163], v[162:163], v[34:35]
	v_lshlrev_b32_e32 v34, 16, v3
	v_and_b32_e32 v35, 0xffff0000, v3
	v_pk_add_f32 v[160:161], v[160:161], v[34:35]
	v_lshlrev_b32_e32 v34, 16, v4
	v_and_b32_e32 v35, 0xffff0000, v4
	v_pk_add_f32 v[158:159], v[158:159], v[34:35]
	v_lshlrev_b32_e32 v34, 16, v5
	v_and_b32_e32 v35, 0xffff0000, v5
	v_pk_add_f32 v[156:157], v[156:157], v[34:35]
	v_lshlrev_b32_e32 v34, 16, v6
	v_and_b32_e32 v35, 0xffff0000, v6
	v_pk_add_f32 v[154:155], v[154:155], v[34:35]
	v_lshlrev_b32_e32 v34, 16, v7
	v_and_b32_e32 v35, 0xffff0000, v7
	v_pk_add_f32 v[152:153], v[152:153], v[34:35]
	v_pk_mul_f32 v[36:37], v[166:167], v[166:167]
	s_nop 0
	v_pk_fma_f32 v[36:37], v[164:165], v[164:165], v[36:37]
	s_nop 0
	v_pk_fma_f32 v[36:37], v[162:163], v[162:163], v[36:37]
	s_nop 0
	v_pk_fma_f32 v[36:37], v[160:161], v[160:161], v[36:37]
	s_nop 0
	v_pk_fma_f32 v[36:37], v[158:159], v[158:159], v[36:37]
	s_nop 0
	v_pk_fma_f32 v[36:37], v[156:157], v[156:157], v[36:37]
	s_nop 0
	v_pk_fma_f32 v[36:37], v[154:155], v[154:155], v[36:37]
	s_nop 0
	v_pk_fma_f32 v[36:37], v[152:153], v[152:153], v[36:37]
	s_nop 0
	v_add_f32_e32 v36, v36, v37
	s_nop 1
	v_add_f32_dpp v36, v36, v36 quad_perm:[1,0,3,2] row_mask:0xf bank_mask:0xf bound_ctrl:1
	s_nop 1
	v_add_f32_dpp v36, v36, v36 quad_perm:[2,3,0,1] row_mask:0xf bank_mask:0xf bound_ctrl:1
	s_nop 1
	v_add_f32_dpp v36, v36, v36 row_half_mirror row_mask:0xf bank_mask:0xf bound_ctrl:1
	s_nop 1
	v_add_f32_dpp v36, v36, v36 row_mirror row_mask:0xf bank_mask:0xf bound_ctrl:1
	v_mov_b32_e32 v37, v36
	s_nop 1
	v_permlane16_swap_b32_e32 v36, v37
	v_add_f32_e32 v36, v36, v37
	v_mov_b32_e32 v37, v36
	s_nop 1
	v_permlane32_swap_b32_e32 v36, v37
	v_add_f32_e32 v36, v36, v37
	s_mov_b32 s36, 0x800000
	v_fmamk_f32 v36, v36, 0x3a800000, v203
	v_mul_f32_e32 v37, 0x4b800000, v36
	v_cmp_gt_f32_e32 vcc, s36, v36
	s_nop 1
	v_cndmask_b32_e32 v36, v36, v37, vcc
	v_rsq_f32_e32 v36, v36
	s_nop 0
	v_mul_f32_e32 v37, 0x45800000, v36
	v_cndmask_b32_e32 v38, v36, v37, vcc
	s_waitcnt vmcnt(0)
	v_pk_mul_f32 v[166:167], v[166:167], v[38:39] op_sel_hi:[1,0]
	v_pk_mul_f32 v[164:165], v[164:165], v[38:39] op_sel_hi:[1,0]
	v_pk_mul_f32 v[162:163], v[162:163], v[38:39] op_sel_hi:[1,0]
	v_pk_mul_f32 v[160:161], v[160:161], v[38:39] op_sel_hi:[1,0]
	v_pk_mul_f32 v[158:159], v[158:159], v[38:39] op_sel_hi:[1,0]
	v_pk_mul_f32 v[156:157], v[156:157], v[38:39] op_sel_hi:[1,0]
	v_pk_mul_f32 v[154:155], v[154:155], v[38:39] op_sel_hi:[1,0]
	v_pk_mul_f32 v[152:153], v[152:153], v[38:39] op_sel_hi:[1,0]
	v_pk_mul_f32 v[40:41], v[166:167], v[8:9]
	v_pk_mul_f32 v[42:43], v[164:165], v[10:11]
	v_pk_mul_f32 v[44:45], v[162:163], v[12:13]
	v_pk_mul_f32 v[46:47], v[160:161], v[14:15]
	v_pk_mul_f32 v[48:49], v[158:159], v[16:17]
	v_pk_mul_f32 v[50:51], v[156:157], v[18:19]
	v_pk_mul_f32 v[52:53], v[154:155], v[20:21]
	v_pk_mul_f32 v[54:55], v[152:153], v[22:23]
	global_store_dwordx4 v[32:33], v[40:43], off
	global_store_dwordx4 v[32:33], v[44:47], off offset:16
	global_store_dwordx4 v[32:33], v[48:51], off offset:32
	global_store_dwordx4 v[32:33], v[52:55], off offset:48
	s_mov_b64 s[50:51], exec
	s_branch .LBB0_753
